# mixer: V^T of the MLA value projection staged through LDS (per-wave 64x128 transpose) and written with 16-byte stores instead of 2-byte scattered stores
# baseline (speedup 1.0000x reference)
; #define LAS __attribute__((address_space(3)))
; __device__ __forceinline__ f32x4 mfma16(bf16x8 a, bf16x8 b, f32x4 c) { return __builtin_amdgcn_mfma_f32_16x16x32_bf16(a, b, c, 0, 0, 0); }
; template <int NKS, int NNT>
; __device__ __forceinline__ void wgemm(f32x4 (&acc)[8][NNT], const LAS bf16_t* A, const int lda, const bf16_t* Bp, const int ldb) {
;     u32x4 bf[NNT][NKS];
; #pragma unroll
;     for (int nt = 0; nt < NNT; ++nt) ldfr(bf[nt], Bp + (size_t)(16 * nt) * ldb);
; #pragma unroll
;     for (int nt = 0; nt < NNT; ++nt) pin(bf[nt]);
; #pragma unroll
;     for (int mt = 0; mt < 8; ++mt) {
;         bf16x8 af[NKS];
; #pragma unroll
;         for (int ks = 0; ks < NKS; ++ks) af[ks] = *(const LAS bf16x8*)(A + (16 * mt) * lda + 32 * ks);
; #pragma unroll
;         for (int nt = 0; nt < NNT; ++nt) { f32x4 a = (f32x4){0.f, 0.f, 0.f, 0.f};
; #pragma unroll
;             for (int ks = 0; ks < NKS; ++ks) a = mfma16(as_bf16x8(bf[nt][ks]), af[ks], a);
;             acc[mt][nt] = a; }
;     }
; __device__ __forceinline__ void mixer_chunk(KP p, LAS unsigned char* lds, int l, int chunk) {
;     ...
;     for (int pz = 0; pz < 2; ++pz) {
;         f32x4 acc[8][2];
;         wgemm<4, 2>(acc, CK + fr * CKLD + 8 * fq, CKLD, (const bf16_t*)(ws + OFF_UKV + l * SZ_UKV) + (size_t)(64 * w + 32 * pz + fr) * 128 + 8 * fq, 128);
.LBB0_320:
	v_and_b32_e32 v249, 63, v204
	v_lshrrev_b32_e32 v248, 4, v249
	v_and_b32_e32 v249, 15, v249
	v_and_b32_e32 v247, 4, v249
	v_lshlrev_b32_e32 v247, 1, v247
	v_and_b32_e32 v246, 8, v249
	v_lshrrev_b32_e32 v246, 1, v246
	v_and_b32_e32 v249, 3, v249
	v_or3_b32 v249, v249, v247, v246
	v_mul_u32_u24_e32 v248, 1056, v248
	v_lshl_add_u32 v251, v249, 1, v248
	v_lshrrev_b32_e32 v250, 7, v204
	v_mul_u32_u24_e32 v250, 0x4200, v250
	v_add_u32_e32 v251, v251, v250
	v_add_u32_e32 v251, 0x15800, v251
	s_mul_i32 s100, s18, 264
	v_add_u32_e32 v251, s100, v251
	v_or_b32_e32 v2, s18, v106
	v_ashrrev_i32_e32 v3, 31, v2
	v_lshlrev_b64 v[2:3], 8, v[2:3]
	v_lshl_add_u64 v[10:11], v[62:63], 0, v[2:3]
	global_load_dwordx4 v[2:5], v[10:11], off
	global_load_dwordx4 v[6:9], v[10:11], off offset:64
	global_load_dwordx4 v[98:101], v[10:11], off offset:128
	global_load_dwordx4 v[108:111], v[10:11], off offset:192
	v_add_co_u32_e32 v10, vcc, 0x1000, v10
	s_mov_b64 s[6:7], -1
	s_nop 0
	v_addc_co_u32_e32 v11, vcc, 0, v11, vcc
	global_load_dwordx4 v[112:115], v[10:11], off
	global_load_dwordx4 v[116:119], v[10:11], off offset:64
	global_load_dwordx4 v[120:123], v[10:11], off offset:128
	global_load_dwordx4 v[124:127], v[10:11], off offset:192
	s_and_b64 vcc, exec, s[90:91]
	s_waitcnt vmcnt(4)
	s_waitcnt vmcnt(0)
	ds_read_b128 v[10:13], v104 offset:51200
	ds_read_b128 v[14:17], v104 offset:51264
	ds_read_b128 v[22:25], v104 offset:55552
	ds_read_b128 v[26:29], v104 offset:55616
	ds_read_b128 v[34:37], v104 offset:59904
	ds_read_b128 v[38:41], v104 offset:59968
	s_waitcnt lgkmcnt(5)
	v_mfma_f32_16x16x32_bf16 v[18:21], v[2:5], v[10:13], 0
	ds_read_b128 v[128:131], v104 offset:64256
	ds_read_b128 v[132:135], v104 offset:64320
	v_mfma_f32_16x16x32_bf16 v[10:13], v[112:115], v[10:13], 0
	s_waitcnt lgkmcnt(5)
	v_mfma_f32_16x16x32_bf16 v[30:33], v[2:5], v[22:25], 0
	v_mfma_f32_16x16x32_bf16 v[22:25], v[112:115], v[22:25], 0
	s_waitcnt lgkmcnt(3)
	v_mfma_f32_16x16x32_bf16 v[42:45], v[2:5], v[34:37], 0
	v_mfma_f32_16x16x32_bf16 v[34:37], v[112:115], v[34:37], 0
	s_waitcnt lgkmcnt(1)
	v_mfma_f32_16x16x32_bf16 v[46:49], v[2:5], v[128:131], 0
	v_mfma_f32_16x16x32_bf16 v[18:21], v[6:9], v[14:17], v[18:21]
	v_mfma_f32_16x16x32_bf16 v[10:13], v[116:119], v[14:17], v[10:13]
	v_mfma_f32_16x16x32_bf16 v[14:17], v[6:9], v[26:29], v[30:33]
	v_mfma_f32_16x16x32_bf16 v[22:25], v[116:119], v[26:29], v[22:25]
	v_mfma_f32_16x16x32_bf16 v[26:29], v[6:9], v[38:41], v[42:45]
	v_mfma_f32_16x16x32_bf16 v[30:33], v[116:119], v[38:41], v[34:37]
	ds_read_b128 v[38:41], v104 offset:51328
	s_nop 0
	ds_read_b128 v[42:45], v104 offset:51392
	s_waitcnt lgkmcnt(2)
	v_mfma_f32_16x16x32_bf16 v[34:37], v[6:9], v[132:135], v[46:49]
	s_waitcnt lgkmcnt(1)
	v_mfma_f32_16x16x32_bf16 v[18:21], v[98:101], v[38:41], v[18:21]
	v_mfma_f32_16x16x32_bf16 v[10:13], v[120:123], v[38:41], v[10:13]
	ds_read_b128 v[38:41], v104 offset:55680
	ds_read_b128 v[46:49], v104 offset:55744
	s_waitcnt lgkmcnt(1)
	v_mfma_f32_16x16x32_bf16 v[14:17], v[98:101], v[38:41], v[14:17]
	v_mfma_f32_16x16x32_bf16 v[22:25], v[120:123], v[38:41], v[22:25]
	ds_read_b128 v[38:41], v104 offset:60032
	ds_read_b128 v[136:139], v104 offset:60096
	v_mfma_f32_16x16x32_bf16 v[58:61], v[124:127], v[42:45], v[10:13]
	s_waitcnt lgkmcnt(2)
	v_mfma_f32_16x16x32_bf16 v[54:57], v[108:111], v[46:49], v[14:17]
	s_nop 0
	ds_read_b128 v[10:13], v104 offset:64384
	s_nop 0
	ds_read_b128 v[14:17], v104 offset:64448
	v_mfma_f32_16x16x32_bf16 v[140:143], v[108:111], v[42:45], v[18:21]
	s_waitcnt lgkmcnt(1)
	v_mfma_f32_16x16x32_bf16 v[18:21], v[98:101], v[10:13], v[34:37]
	v_mfma_f32_16x16x32_bf16 v[26:29], v[98:101], v[38:41], v[26:29]
	v_mfma_f32_16x16x32_bf16 v[30:33], v[120:123], v[38:41], v[30:33]
	s_waitcnt lgkmcnt(0)
	v_mfma_f32_16x16x32_bf16 v[38:41], v[108:111], v[14:17], v[18:21]
	v_mfma_f32_16x16x32_bf16 v[18:21], v[112:115], v[128:131], 0
	v_mfma_f32_16x16x32_bf16 v[18:21], v[116:119], v[132:135], v[18:21]
	v_mfma_f32_16x16x32_bf16 v[10:13], v[120:123], v[10:13], v[18:21]
	v_mfma_f32_16x16x32_bf16 v[34:37], v[124:127], v[14:17], v[10:13]
	s_nop 6
	ds_read_b128 v[10:13], v105 offset:17408
	ds_read_b128 v[14:17], v105 offset:17472
	s_waitcnt lgkmcnt(1)
; #define LAS __attribute__((address_space(3)))
; __device__ __forceinline__ unsigned pk2(float lo, float hi) { unsigned r; asm("v_cvt_pk_bf16_f32 %0, %1, %2" : "=v"(r) : "v"(lo), "v"(hi)); return r; }
; __device__ __forceinline__ f32x4 mfma16(bf16x8 a, bf16x8 b, f32x4 c) { return __builtin_amdgcn_mfma_f32_16x16x32_bf16(a, b, c, 0, 0, 0); }
; template <int NKS, int NNT>
; __device__ __forceinline__ void wgemm(f32x4 (&acc)[8][NNT], const LAS bf16_t* A, const int lda, const bf16_t* Bp, const int ldb) {
;     ...
; #pragma unroll
;     for (int mt = 0; mt < 8; ++mt) {
;         bf16x8 af[NKS];
; #pragma unroll
;         for (int ks = 0; ks < NKS; ++ks) af[ks] = *(const LAS bf16x8*)(A + (16 * mt) * lda + 32 * ks);
; #pragma unroll
;         for (int nt = 0; nt < NNT; ++nt) { f32x4 a = (f32x4){0.f, 0.f, 0.f, 0.f};
; #pragma unroll
;             for (int ks = 0; ks < NKS; ++ks) a = mfma16(as_bf16x8(bf[nt][ks]), af[ks], a);
;             acc[mt][nt] = a; }
;     }
; __device__ __forceinline__ void mixer_chunk(KP p, LAS unsigned char* lds, int l, int chunk) {
;     ...
;         const int head = w >> 1;
; #pragma unroll
;         for (int mt = 0; mt < 8; ++mt) {
;             const float rs = RSK[16 * mt + fr]; const int spos = s0 + 16 * mt + fr;
; #pragma unroll
;             for (int n = 0; n < 2; ++n) {
;                 const f32x4 a = acc[mt][n] * rs; const unsigned p0 = pk2(a[0], a[1]), p1 = pk2(a[2], a[3]);
;                 if ((w & 1) == 0) { u32x2 o; o.x = p0; o.y = p1; *(u32x2*)((bf16_t*)(ws + OFF_K) + ((size_t)(bidx * 4 + head) * SEQ + spos) * 96 + 16 * (2 * pz + n) + 4 * fq) = o; }
;                 else { const int fp = ((fr & 4) << 1) | ((fr & 8) >> 1) | (fr & 3);
;                     bf16_t* vv = (bf16_t*)(ws + OFF_VT) + ((size_t)(bidx * 4 + head) * 64 + 16 * (2 * pz + n) + 4 * fq) * SEQ + (spos - fr + fp);
;                     vv[0] = (bf16_t)(p0 & 0xffff); vv[SEQ] = (bf16_t)(p0 >> 16); vv[2 * SEQ] = (bf16_t)(p1 & 0xffff); vv[3 * SEQ] = (bf16_t)(p1 >> 16); }
	v_mfma_f32_16x16x32_bf16 v[18:21], v[2:5], v[10:13], 0
	v_mfma_f32_16x16x32_bf16 v[10:13], v[112:115], v[10:13], 0
	v_mfma_f32_16x16x32_bf16 v[50:53], v[124:127], v[46:49], v[22:25]
	v_mfma_f32_16x16x32_bf16 v[46:49], v[108:111], v[136:139], v[26:29]
	s_nop 1
	ds_read_b128 v[22:25], v105 offset:17536
	ds_read_b128 v[26:29], v105 offset:17600
	s_waitcnt lgkmcnt(2)
	v_mfma_f32_16x16x32_bf16 v[18:21], v[6:9], v[14:17], v[18:21]
	v_mfma_f32_16x16x32_bf16 v[10:13], v[116:119], v[14:17], v[10:13]
	s_waitcnt lgkmcnt(1)
	v_mfma_f32_16x16x32_bf16 v[18:21], v[98:101], v[22:25], v[18:21]
	v_mfma_f32_16x16x32_bf16 v[10:13], v[120:123], v[22:25], v[10:13]
	v_mfma_f32_16x16x32_bf16 v[42:45], v[124:127], v[136:139], v[30:33]
	s_waitcnt lgkmcnt(0)
	v_mfma_f32_16x16x32_bf16 v[30:33], v[108:111], v[26:29], v[18:21]
	v_mfma_f32_16x16x32_bf16 v[26:29], v[124:127], v[26:29], v[10:13]
	s_nop 3
	ds_read_b128 v[10:13], v105 offset:21760
	ds_read_b128 v[14:17], v105 offset:21824
	ds_read_b128 v[128:131], v105 offset:21888
	ds_read_b128 v[132:135], v105 offset:21952
	s_waitcnt lgkmcnt(3)
	v_mfma_f32_16x16x32_bf16 v[18:21], v[2:5], v[10:13], 0
	v_mfma_f32_16x16x32_bf16 v[10:13], v[112:115], v[10:13], 0
	s_waitcnt lgkmcnt(2)
	v_mfma_f32_16x16x32_bf16 v[18:21], v[6:9], v[14:17], v[18:21]
	v_mfma_f32_16x16x32_bf16 v[10:13], v[116:119], v[14:17], v[10:13]
	s_waitcnt lgkmcnt(1)
	v_mfma_f32_16x16x32_bf16 v[18:21], v[98:101], v[128:131], v[18:21]
	v_mfma_f32_16x16x32_bf16 v[10:13], v[120:123], v[128:131], v[10:13]
	s_waitcnt lgkmcnt(0)
	v_mfma_f32_16x16x32_bf16 v[22:25], v[108:111], v[132:135], v[18:21]
	v_mfma_f32_16x16x32_bf16 v[18:21], v[124:127], v[132:135], v[10:13]
	s_nop 4
	ds_read_b128 v[10:13], v105 offset:26112
	ds_read_b128 v[128:131], v105 offset:26176
	ds_read_b128 v[132:135], v105 offset:26240
	ds_read_b128 v[136:139], v105 offset:26304
	s_waitcnt lgkmcnt(3)
	v_mfma_f32_16x16x32_bf16 v[14:17], v[2:5], v[10:13], 0
	v_mfma_f32_16x16x32_bf16 v[10:13], v[112:115], v[10:13], 0
	s_waitcnt lgkmcnt(2)
	v_mfma_f32_16x16x32_bf16 v[14:17], v[6:9], v[128:131], v[14:17]
	v_mfma_f32_16x16x32_bf16 v[10:13], v[116:119], v[128:131], v[10:13]
	s_waitcnt lgkmcnt(1)
	v_mfma_f32_16x16x32_bf16 v[14:17], v[98:101], v[132:135], v[14:17]
	v_mfma_f32_16x16x32_bf16 v[10:13], v[120:123], v[132:135], v[10:13]
	ds_read_b128 v[128:131], v105 offset:30464
	ds_read_b128 v[132:135], v105 offset:30528
	s_waitcnt lgkmcnt(1)
	v_mfma_f32_16x16x32_bf16 v[2:5], v[2:5], v[128:131], 0
	v_mfma_f32_16x16x32_bf16 v[14:17], v[108:111], v[136:139], v[14:17]
	v_mfma_f32_16x16x32_bf16 v[10:13], v[124:127], v[136:139], v[10:13]
	ds_read_b128 v[136:139], v105 offset:30592
	ds_read_b128 v[144:147], v105 offset:30656
	s_waitcnt lgkmcnt(2)
	v_mfma_f32_16x16x32_bf16 v[2:5], v[6:9], v[132:135], v[2:5]
	s_waitcnt lgkmcnt(1)
	v_mfma_f32_16x16x32_bf16 v[2:5], v[98:101], v[136:139], v[2:5]
	ds_read_b32 v100, v107
	s_waitcnt lgkmcnt(0)
	v_pk_mul_f32 v[98:99], v[142:143], v[100:101] op_sel_hi:[1,0]
	v_mfma_f32_16x16x32_bf16 v[6:9], v[108:111], v[144:147], v[2:5]
	v_mul_f32_e64 v102, v140, v100
	v_mul_f32_e64 v103, v141, v100
	v_cvt_pk_bf16_f32 v102, v102, v103
	v_mfma_f32_16x16x32_bf16 v[2:5], v[112:115], v[128:131], 0
	v_cvt_pk_bf16_f32 v103, v98, v99
	v_or_b32_e32 v98, s18, v64
	v_mfma_f32_16x16x32_bf16 v[2:5], v[116:119], v[132:135], v[2:5]
	v_mfma_f32_16x16x32_bf16 v[2:5], v[120:123], v[136:139], v[2:5]
	v_mfma_f32_16x16x32_bf16 v[2:5], v[124:127], v[144:147], v[2:5]
	s_cbranch_vccz .LBB0_322
	v_mov_b32_e32 v99, v65
	v_lshlrev_b64 v[108:109], 13, v[98:99]
	v_lshl_add_u64 v[108:109], v[66:67], 0, v[108:109]
	v_add_co_u32_e32 v110, vcc, 0x2000, v108
	ds_write_b16 v251, v102 offset:0
	s_nop 0
	v_addc_co_u32_e32 v111, vcc, 0, v109, vcc
	ds_write_b16_d16_hi v251, v102 offset:264
	v_add_co_u32_e32 v110, vcc, 0x4000, v108
	s_mov_b64 s[6:7], 0
	s_nop 0
	v_addc_co_u32_e32 v111, vcc, 0, v109, vcc
	v_add_co_u32_e32 v108, vcc, 0x6000, v108
	ds_write_b16 v251, v103 offset:528
	s_nop 0
	v_addc_co_u32_e32 v109, vcc, 0, v109, vcc
	ds_write_b16_d16_hi v251, v103 offset:792

; __device__ __forceinline__ unsigned pk2(float lo, float hi) { unsigned r; asm("v_cvt_pk_bf16_f32 %0, %1, %2" : "=v"(r) : "v"(lo), "v"(hi)); return r; }
; __device__ __forceinline__ void mixer_chunk(KP p, LAS unsigned char* lds, int l, int chunk) {
;     ...
;         for (int mt = 0; mt < 8; ++mt) {
;             const float rs = RSK[16 * mt + fr]; const int spos = s0 + 16 * mt + fr;
; #pragma unroll
;             for (int n = 0; n < 2; ++n) {
;                 const f32x4 a = acc[mt][n] * rs; const unsigned p0 = pk2(a[0], a[1]), p1 = pk2(a[2], a[3]);
;                 if ((w & 1) == 0) { u32x2 o; o.x = p0; o.y = p1; *(u32x2*)((bf16_t*)(ws + OFF_K) + ((size_t)(bidx * 4 + head) * SEQ + spos) * 96 + 16 * (2 * pz + n) + 4 * fq) = o; }
;                 else { const int fp = ((fr & 4) << 1) | ((fr & 8) >> 1) | (fr & 3);
;                     bf16_t* vv = (bf16_t*)(ws + OFF_VT) + ((size_t)(bidx * 4 + head) * 64 + 16 * (2 * pz + n) + 4 * fq) * SEQ + (spos - fr + fp);
;                     vv[0] = (bf16_t)(p0 & 0xffff); vv[SEQ] = (bf16_t)(p0 >> 16); vv[2 * SEQ] = (bf16_t)(p1 & 0xffff); vv[3 * SEQ] = (bf16_t)(p1 >> 16); }
.LBB0_324:
	v_mov_b32_e32 v101, v100
	v_mov_b32_e32 v102, v100
	v_mov_b32_e32 v103, v100
	v_pk_mul_f32 v[58:59], v[58:59], v[100:101]
	v_pk_mul_f32 v[102:103], v[60:61], v[102:103]
	v_cvt_pk_bf16_f32 v60, v58, v59
	v_cndmask_b32_e64 v58, 0, 1, s[90:91]
	s_mov_b64 s[6:7], -1
	v_cmp_ne_u32_e64 s[42:43], 1, v58
	s_andn2_b64 vcc, exec, s[90:91]
	v_or3_b32 v58, s18, 16, v64
	v_cvt_pk_bf16_f32 v61, v102, v103
	s_cbranch_vccnz .LBB0_326
	v_mov_b32_e32 v59, v65
	v_lshlrev_b64 v[100:101], 13, v[58:59]
	v_lshl_add_u64 v[100:101], v[66:67], 0, v[100:101]
	v_add_co_u32_e32 v102, vcc, 0x2000, v100
	ds_write_b16 v251, v60 offset:4224
	s_nop 0
	v_addc_co_u32_e32 v103, vcc, 0, v101, vcc
	ds_write_b16_d16_hi v251, v60 offset:4488
	v_add_co_u32_e32 v102, vcc, 0x4000, v100
	s_mov_b64 s[6:7], 0
	s_nop 0
	v_addc_co_u32_e32 v103, vcc, 0, v101, vcc
	v_add_co_u32_e32 v100, vcc, 0x6000, v100
	ds_write_b16 v251, v61 offset:4752
	s_nop 0
	v_addc_co_u32_e32 v101, vcc, 0, v101, vcc
	ds_write_b16_d16_hi v251, v61 offset:5016

; __device__ __forceinline__ unsigned pk2(float lo, float hi) { unsigned r; asm("v_cvt_pk_bf16_f32 %0, %1, %2" : "=v"(r) : "v"(lo), "v"(hi)); return r; }
; __device__ __forceinline__ void mixer_chunk(KP p, LAS unsigned char* lds, int l, int chunk) {
;     ...
;         for (int mt = 0; mt < 8; ++mt) {
;             const float rs = RSK[16 * mt + fr]; const int spos = s0 + 16 * mt + fr;
; #pragma unroll
;             for (int n = 0; n < 2; ++n) {
;                 const f32x4 a = acc[mt][n] * rs; const unsigned p0 = pk2(a[0], a[1]), p1 = pk2(a[2], a[3]);
;                 if ((w & 1) == 0) { u32x2 o; o.x = p0; o.y = p1; *(u32x2*)((bf16_t*)(ws + OFF_K) + ((size_t)(bidx * 4 + head) * SEQ + spos) * 96 + 16 * (2 * pz + n) + 4 * fq) = o; }
;                 else { const int fp = ((fr & 4) << 1) | ((fr & 8) >> 1) | (fr & 3);
;                     bf16_t* vv = (bf16_t*)(ws + OFF_VT) + ((size_t)(bidx * 4 + head) * 64 + 16 * (2 * pz + n) + 4 * fq) * SEQ + (spos - fr + fp);
;                     vv[0] = (bf16_t)(p0 & 0xffff); vv[SEQ] = (bf16_t)(p0 >> 16); vv[2 * SEQ] = (bf16_t)(p1 & 0xffff); vv[3 * SEQ] = (bf16_t)(p1 >> 16); }
.LBB0_328:
	ds_read_b32 v60, v107 offset:64
	s_and_b64 vcc, exec, s[42:43]
	s_mov_b64 s[6:7], -1
	s_waitcnt lgkmcnt(0)
	v_pk_mul_f32 v[54:55], v[54:55], v[60:61] op_sel_hi:[1,0]
	v_pk_mul_f32 v[56:57], v[56:57], v[60:61] op_sel_hi:[1,0]
	v_cvt_pk_bf16_f32 v54, v54, v55
	s_nop 0
	v_cvt_pk_bf16_f32 v55, v56, v57
	s_cbranch_vccnz .LBB0_330
	v_mov_b32_e32 v99, v65
	v_lshlrev_b64 v[56:57], 13, v[98:99]
	v_lshl_add_u64 v[56:57], v[84:85], 0, v[56:57]
	v_add_co_u32_e32 v100, vcc, 0x2000, v56
	ds_write_b16 v251, v54 offset:32
	s_nop 0
	v_addc_co_u32_e32 v101, vcc, 0, v57, vcc
	ds_write_b16_d16_hi v251, v54 offset:296
	v_add_co_u32_e32 v100, vcc, 0x4000, v56
	s_mov_b64 s[6:7], 0
	s_nop 0
	v_addc_co_u32_e32 v101, vcc, 0, v57, vcc
	v_add_co_u32_e32 v56, vcc, 0x6000, v56
	ds_write_b16 v251, v55 offset:560
	s_nop 0
	v_addc_co_u32_e32 v57, vcc, 0, v57, vcc
	ds_write_b16_d16_hi v251, v55 offset:824

; __device__ __forceinline__ unsigned pk2(float lo, float hi) { unsigned r; asm("v_cvt_pk_bf16_f32 %0, %1, %2" : "=v"(r) : "v"(lo), "v"(hi)); return r; }
; __device__ __forceinline__ void mixer_chunk(KP p, LAS unsigned char* lds, int l, int chunk) {
;     ...
;         for (int mt = 0; mt < 8; ++mt) {
;             const float rs = RSK[16 * mt + fr]; const int spos = s0 + 16 * mt + fr;
; #pragma unroll
;             for (int n = 0; n < 2; ++n) {
;                 const f32x4 a = acc[mt][n] * rs; const unsigned p0 = pk2(a[0], a[1]), p1 = pk2(a[2], a[3]);
;                 if ((w & 1) == 0) { u32x2 o; o.x = p0; o.y = p1; *(u32x2*)((bf16_t*)(ws + OFF_K) + ((size_t)(bidx * 4 + head) * SEQ + spos) * 96 + 16 * (2 * pz + n) + 4 * fq) = o; }
;                 else { const int fp = ((fr & 4) << 1) | ((fr & 8) >> 1) | (fr & 3);
;                     bf16_t* vv = (bf16_t*)(ws + OFF_VT) + ((size_t)(bidx * 4 + head) * 64 + 16 * (2 * pz + n) + 4 * fq) * SEQ + (spos - fr + fp);
;                     vv[0] = (bf16_t)(p0 & 0xffff); vv[SEQ] = (bf16_t)(p0 >> 16); vv[2 * SEQ] = (bf16_t)(p1 & 0xffff); vv[3 * SEQ] = (bf16_t)(p1 >> 16); }
.LBB0_332:
	v_mov_b32_e32 v61, v60
	v_mov_b32_e32 v54, v60
	v_mov_b32_e32 v55, v60
	v_pk_mul_f32 v[50:51], v[50:51], v[60:61]
	s_and_b64 vcc, exec, s[42:43]
	s_mov_b64 s[6:7], -1
	v_pk_mul_f32 v[52:53], v[52:53], v[54:55]
	v_cvt_pk_bf16_f32 v50, v50, v51
	s_nop 0
	v_cvt_pk_bf16_f32 v51, v52, v53
	s_cbranch_vccnz .LBB0_334
	v_mov_b32_e32 v59, v65
	v_lshlrev_b64 v[52:53], 13, v[58:59]
	v_lshl_add_u64 v[52:53], v[84:85], 0, v[52:53]
	v_add_co_u32_e32 v54, vcc, 0x2000, v52
	ds_write_b16 v251, v50 offset:4256
	s_nop 0
	v_addc_co_u32_e32 v55, vcc, 0, v53, vcc
	ds_write_b16_d16_hi v251, v50 offset:4520
	v_add_co_u32_e32 v54, vcc, 0x4000, v52
	s_mov_b64 s[6:7], 0
	s_nop 0
	v_addc_co_u32_e32 v55, vcc, 0, v53, vcc
	v_add_co_u32_e32 v52, vcc, 0x6000, v52
	ds_write_b16 v251, v51 offset:4784
	s_nop 0
	v_addc_co_u32_e32 v53, vcc, 0, v53, vcc
	ds_write_b16_d16_hi v251, v51 offset:5048

; __device__ __forceinline__ unsigned pk2(float lo, float hi) { unsigned r; asm("v_cvt_pk_bf16_f32 %0, %1, %2" : "=v"(r) : "v"(lo), "v"(hi)); return r; }
; __device__ __forceinline__ void mixer_chunk(KP p, LAS unsigned char* lds, int l, int chunk) {
;     ...
;         for (int mt = 0; mt < 8; ++mt) {
;             const float rs = RSK[16 * mt + fr]; const int spos = s0 + 16 * mt + fr;
; #pragma unroll
;             for (int n = 0; n < 2; ++n) {
;                 const f32x4 a = acc[mt][n] * rs; const unsigned p0 = pk2(a[0], a[1]), p1 = pk2(a[2], a[3]);
;                 if ((w & 1) == 0) { u32x2 o; o.x = p0; o.y = p1; *(u32x2*)((bf16_t*)(ws + OFF_K) + ((size_t)(bidx * 4 + head) * SEQ + spos) * 96 + 16 * (2 * pz + n) + 4 * fq) = o; }
;                 else { const int fp = ((fr & 4) << 1) | ((fr & 8) >> 1) | (fr & 3);
;                     bf16_t* vv = (bf16_t*)(ws + OFF_VT) + ((size_t)(bidx * 4 + head) * 64 + 16 * (2 * pz + n) + 4 * fq) * SEQ + (spos - fr + fp);
;                     vv[0] = (bf16_t)(p0 & 0xffff); vv[SEQ] = (bf16_t)(p0 >> 16); vv[2 * SEQ] = (bf16_t)(p1 & 0xffff); vv[3 * SEQ] = (bf16_t)(p1 >> 16); }
.LBB0_336:
	ds_read_b32 v50, v107 offset:128
	s_and_b64 vcc, exec, s[42:43]
	s_mov_b64 s[6:7], -1
	s_waitcnt lgkmcnt(0)
	v_pk_mul_f32 v[46:47], v[46:47], v[50:51] op_sel_hi:[1,0]
	v_pk_mul_f32 v[48:49], v[48:49], v[50:51] op_sel_hi:[1,0]
	v_cvt_pk_bf16_f32 v46, v46, v47
	s_nop 0
	v_cvt_pk_bf16_f32 v47, v48, v49
	s_cbranch_vccnz .LBB0_338
	v_mov_b32_e32 v99, v65
	v_lshlrev_b64 v[48:49], 13, v[98:99]
	v_lshl_add_u64 v[48:49], v[86:87], 0, v[48:49]
	v_add_co_u32_e32 v52, vcc, 0x2000, v48
	ds_write_b16 v251, v46 offset:64
	s_nop 0
	v_addc_co_u32_e32 v53, vcc, 0, v49, vcc
	ds_write_b16_d16_hi v251, v46 offset:328
	v_add_co_u32_e32 v52, vcc, 0x4000, v48
	s_mov_b64 s[6:7], 0
	s_nop 0
	v_addc_co_u32_e32 v53, vcc, 0, v49, vcc
	v_add_co_u32_e32 v48, vcc, 0x6000, v48
	ds_write_b16 v251, v47 offset:592
	s_nop 0
	v_addc_co_u32_e32 v49, vcc, 0, v49, vcc
	ds_write_b16_d16_hi v251, v47 offset:856

; __device__ __forceinline__ unsigned pk2(float lo, float hi) { unsigned r; asm("v_cvt_pk_bf16_f32 %0, %1, %2" : "=v"(r) : "v"(lo), "v"(hi)); return r; }
; __device__ __forceinline__ void mixer_chunk(KP p, LAS unsigned char* lds, int l, int chunk) {
;     ...
;         for (int mt = 0; mt < 8; ++mt) {
;             const float rs = RSK[16 * mt + fr]; const int spos = s0 + 16 * mt + fr;
; #pragma unroll
;             for (int n = 0; n < 2; ++n) {
;                 const f32x4 a = acc[mt][n] * rs; const unsigned p0 = pk2(a[0], a[1]), p1 = pk2(a[2], a[3]);
;                 if ((w & 1) == 0) { u32x2 o; o.x = p0; o.y = p1; *(u32x2*)((bf16_t*)(ws + OFF_K) + ((size_t)(bidx * 4 + head) * SEQ + spos) * 96 + 16 * (2 * pz + n) + 4 * fq) = o; }
;                 else { const int fp = ((fr & 4) << 1) | ((fr & 8) >> 1) | (fr & 3);
;                     bf16_t* vv = (bf16_t*)(ws + OFF_VT) + ((size_t)(bidx * 4 + head) * 64 + 16 * (2 * pz + n) + 4 * fq) * SEQ + (spos - fr + fp);
;                     vv[0] = (bf16_t)(p0 & 0xffff); vv[SEQ] = (bf16_t)(p0 >> 16); vv[2 * SEQ] = (bf16_t)(p1 & 0xffff); vv[3 * SEQ] = (bf16_t)(p1 >> 16); }
.LBB0_340:
	v_mov_b32_e32 v51, v50
	v_mov_b32_e32 v46, v50
	v_mov_b32_e32 v47, v50
	v_pk_mul_f32 v[42:43], v[42:43], v[50:51]
	s_and_b64 vcc, exec, s[42:43]
	s_mov_b64 s[6:7], -1
	v_pk_mul_f32 v[44:45], v[44:45], v[46:47]
	v_cvt_pk_bf16_f32 v42, v42, v43
	s_nop 0
	v_cvt_pk_bf16_f32 v43, v44, v45
	s_cbranch_vccnz .LBB0_342
	v_mov_b32_e32 v59, v65
	v_lshlrev_b64 v[44:45], 13, v[58:59]
	v_lshl_add_u64 v[44:45], v[86:87], 0, v[44:45]
	v_add_co_u32_e32 v46, vcc, 0x2000, v44
	ds_write_b16 v251, v42 offset:4288
	s_nop 0
	v_addc_co_u32_e32 v47, vcc, 0, v45, vcc
	ds_write_b16_d16_hi v251, v42 offset:4552
	v_add_co_u32_e32 v46, vcc, 0x4000, v44
	s_mov_b64 s[6:7], 0
	s_nop 0
	v_addc_co_u32_e32 v47, vcc, 0, v45, vcc
	v_add_co_u32_e32 v44, vcc, 0x6000, v44
	ds_write_b16 v251, v43 offset:4816
	s_nop 0
	v_addc_co_u32_e32 v45, vcc, 0, v45, vcc
	ds_write_b16_d16_hi v251, v43 offset:5080

; __device__ __forceinline__ unsigned pk2(float lo, float hi) { unsigned r; asm("v_cvt_pk_bf16_f32 %0, %1, %2" : "=v"(r) : "v"(lo), "v"(hi)); return r; }
; __device__ __forceinline__ void mixer_chunk(KP p, LAS unsigned char* lds, int l, int chunk) {
;     ...
;         for (int mt = 0; mt < 8; ++mt) {
;             const float rs = RSK[16 * mt + fr]; const int spos = s0 + 16 * mt + fr;
; #pragma unroll
;             for (int n = 0; n < 2; ++n) {
;                 const f32x4 a = acc[mt][n] * rs; const unsigned p0 = pk2(a[0], a[1]), p1 = pk2(a[2], a[3]);
;                 if ((w & 1) == 0) { u32x2 o; o.x = p0; o.y = p1; *(u32x2*)((bf16_t*)(ws + OFF_K) + ((size_t)(bidx * 4 + head) * SEQ + spos) * 96 + 16 * (2 * pz + n) + 4 * fq) = o; }
;                 else { const int fp = ((fr & 4) << 1) | ((fr & 8) >> 1) | (fr & 3);
;                     bf16_t* vv = (bf16_t*)(ws + OFF_VT) + ((size_t)(bidx * 4 + head) * 64 + 16 * (2 * pz + n) + 4 * fq) * SEQ + (spos - fr + fp);
;                     vv[0] = (bf16_t)(p0 & 0xffff); vv[SEQ] = (bf16_t)(p0 >> 16); vv[2 * SEQ] = (bf16_t)(p1 & 0xffff); vv[3 * SEQ] = (bf16_t)(p1 >> 16); }
.LBB0_344:
	ds_read_b32 v42, v107 offset:192
	s_and_b64 vcc, exec, s[42:43]
	s_mov_b64 s[6:7], -1
	s_waitcnt lgkmcnt(0)
	v_pk_mul_f32 v[38:39], v[38:39], v[42:43] op_sel_hi:[1,0]
	v_pk_mul_f32 v[40:41], v[40:41], v[42:43] op_sel_hi:[1,0]
	v_cvt_pk_bf16_f32 v38, v38, v39
	s_nop 0
	v_cvt_pk_bf16_f32 v39, v40, v41
	s_cbranch_vccnz .LBB0_346
	v_mov_b32_e32 v99, v65
	v_lshlrev_b64 v[40:41], 13, v[98:99]
	v_lshl_add_u64 v[40:41], v[88:89], 0, v[40:41]
	v_add_co_u32_e32 v44, vcc, 0x2000, v40
	ds_write_b16 v251, v38 offset:96
	s_nop 0
	v_addc_co_u32_e32 v45, vcc, 0, v41, vcc
	ds_write_b16_d16_hi v251, v38 offset:360
	v_add_co_u32_e32 v44, vcc, 0x4000, v40
	s_mov_b64 s[6:7], 0
	s_nop 0
	v_addc_co_u32_e32 v45, vcc, 0, v41, vcc
	v_add_co_u32_e32 v40, vcc, 0x6000, v40
	ds_write_b16 v251, v39 offset:624
	s_nop 0
	v_addc_co_u32_e32 v41, vcc, 0, v41, vcc
	ds_write_b16_d16_hi v251, v39 offset:888

; __device__ __forceinline__ unsigned pk2(float lo, float hi) { unsigned r; asm("v_cvt_pk_bf16_f32 %0, %1, %2" : "=v"(r) : "v"(lo), "v"(hi)); return r; }
; __device__ __forceinline__ void mixer_chunk(KP p, LAS unsigned char* lds, int l, int chunk) {
;     ...
;         for (int mt = 0; mt < 8; ++mt) {
;             const float rs = RSK[16 * mt + fr]; const int spos = s0 + 16 * mt + fr;
; #pragma unroll
;             for (int n = 0; n < 2; ++n) {
;                 const f32x4 a = acc[mt][n] * rs; const unsigned p0 = pk2(a[0], a[1]), p1 = pk2(a[2], a[3]);
;                 if ((w & 1) == 0) { u32x2 o; o.x = p0; o.y = p1; *(u32x2*)((bf16_t*)(ws + OFF_K) + ((size_t)(bidx * 4 + head) * SEQ + spos) * 96 + 16 * (2 * pz + n) + 4 * fq) = o; }
;                 else { const int fp = ((fr & 4) << 1) | ((fr & 8) >> 1) | (fr & 3);
;                     bf16_t* vv = (bf16_t*)(ws + OFF_VT) + ((size_t)(bidx * 4 + head) * 64 + 16 * (2 * pz + n) + 4 * fq) * SEQ + (spos - fr + fp);
;                     vv[0] = (bf16_t)(p0 & 0xffff); vv[SEQ] = (bf16_t)(p0 >> 16); vv[2 * SEQ] = (bf16_t)(p1 & 0xffff); vv[3 * SEQ] = (bf16_t)(p1 >> 16); }
.LBB0_348:
	v_mov_b32_e32 v43, v42
	v_mov_b32_e32 v38, v42
	v_mov_b32_e32 v39, v42
	v_pk_mul_f32 v[34:35], v[34:35], v[42:43]
	s_and_b64 vcc, exec, s[42:43]
	s_mov_b64 s[6:7], -1
	v_pk_mul_f32 v[36:37], v[36:37], v[38:39]
	v_cvt_pk_bf16_f32 v34, v34, v35
	s_nop 0
	v_cvt_pk_bf16_f32 v35, v36, v37
	s_cbranch_vccnz .LBB0_350
	v_mov_b32_e32 v59, v65
	v_lshlrev_b64 v[36:37], 13, v[58:59]
	v_lshl_add_u64 v[36:37], v[88:89], 0, v[36:37]
	v_add_co_u32_e32 v38, vcc, 0x2000, v36
	ds_write_b16 v251, v34 offset:4320
	s_nop 0
	v_addc_co_u32_e32 v39, vcc, 0, v37, vcc
	ds_write_b16_d16_hi v251, v34 offset:4584
	v_add_co_u32_e32 v38, vcc, 0x4000, v36
	s_mov_b64 s[6:7], 0
	s_nop 0
	v_addc_co_u32_e32 v39, vcc, 0, v37, vcc
	v_add_co_u32_e32 v36, vcc, 0x6000, v36
	ds_write_b16 v251, v35 offset:4848
	s_nop 0
	v_addc_co_u32_e32 v37, vcc, 0, v37, vcc
	ds_write_b16_d16_hi v251, v35 offset:5112

; __device__ __forceinline__ unsigned pk2(float lo, float hi) { unsigned r; asm("v_cvt_pk_bf16_f32 %0, %1, %2" : "=v"(r) : "v"(lo), "v"(hi)); return r; }
; __device__ __forceinline__ void mixer_chunk(KP p, LAS unsigned char* lds, int l, int chunk) {
;     ...
;         for (int mt = 0; mt < 8; ++mt) {
;             const float rs = RSK[16 * mt + fr]; const int spos = s0 + 16 * mt + fr;
; #pragma unroll
;             for (int n = 0; n < 2; ++n) {
;                 const f32x4 a = acc[mt][n] * rs; const unsigned p0 = pk2(a[0], a[1]), p1 = pk2(a[2], a[3]);
;                 if ((w & 1) == 0) { u32x2 o; o.x = p0; o.y = p1; *(u32x2*)((bf16_t*)(ws + OFF_K) + ((size_t)(bidx * 4 + head) * SEQ + spos) * 96 + 16 * (2 * pz + n) + 4 * fq) = o; }
;                 else { const int fp = ((fr & 4) << 1) | ((fr & 8) >> 1) | (fr & 3);
;                     bf16_t* vv = (bf16_t*)(ws + OFF_VT) + ((size_t)(bidx * 4 + head) * 64 + 16 * (2 * pz + n) + 4 * fq) * SEQ + (spos - fr + fp);
;                     vv[0] = (bf16_t)(p0 & 0xffff); vv[SEQ] = (bf16_t)(p0 >> 16); vv[2 * SEQ] = (bf16_t)(p1 & 0xffff); vv[3 * SEQ] = (bf16_t)(p1 >> 16); }
.LBB0_352:
	ds_read_b32 v34, v107 offset:256
	s_and_b64 vcc, exec, s[42:43]
	s_mov_b64 s[6:7], -1
	s_waitcnt lgkmcnt(0)
	v_pk_mul_f32 v[30:31], v[30:31], v[34:35] op_sel_hi:[1,0]
	v_pk_mul_f32 v[32:33], v[32:33], v[34:35] op_sel_hi:[1,0]
	v_cvt_pk_bf16_f32 v30, v30, v31
	s_nop 0
	v_cvt_pk_bf16_f32 v31, v32, v33
	s_cbranch_vccnz .LBB0_354
	v_mov_b32_e32 v99, v65
	v_lshlrev_b64 v[32:33], 13, v[98:99]
	v_lshl_add_u64 v[32:33], v[90:91], 0, v[32:33]
	v_add_co_u32_e32 v36, vcc, 0x2000, v32
	ds_write_b16 v251, v30 offset:128
	s_nop 0
	v_addc_co_u32_e32 v37, vcc, 0, v33, vcc
	ds_write_b16_d16_hi v251, v30 offset:392
	v_add_co_u32_e32 v36, vcc, 0x4000, v32
	s_mov_b64 s[6:7], 0
	s_nop 0
	v_addc_co_u32_e32 v37, vcc, 0, v33, vcc
	v_add_co_u32_e32 v32, vcc, 0x6000, v32
	ds_write_b16 v251, v31 offset:656
	s_nop 0
	v_addc_co_u32_e32 v33, vcc, 0, v33, vcc
	ds_write_b16_d16_hi v251, v31 offset:920

; __device__ __forceinline__ unsigned pk2(float lo, float hi) { unsigned r; asm("v_cvt_pk_bf16_f32 %0, %1, %2" : "=v"(r) : "v"(lo), "v"(hi)); return r; }
; __device__ __forceinline__ void mixer_chunk(KP p, LAS unsigned char* lds, int l, int chunk) {
;     ...
;         for (int mt = 0; mt < 8; ++mt) {
;             const float rs = RSK[16 * mt + fr]; const int spos = s0 + 16 * mt + fr;
; #pragma unroll
;             for (int n = 0; n < 2; ++n) {
;                 const f32x4 a = acc[mt][n] * rs; const unsigned p0 = pk2(a[0], a[1]), p1 = pk2(a[2], a[3]);
;                 if ((w & 1) == 0) { u32x2 o; o.x = p0; o.y = p1; *(u32x2*)((bf16_t*)(ws + OFF_K) + ((size_t)(bidx * 4 + head) * SEQ + spos) * 96 + 16 * (2 * pz + n) + 4 * fq) = o; }
;                 else { const int fp = ((fr & 4) << 1) | ((fr & 8) >> 1) | (fr & 3);
;                     bf16_t* vv = (bf16_t*)(ws + OFF_VT) + ((size_t)(bidx * 4 + head) * 64 + 16 * (2 * pz + n) + 4 * fq) * SEQ + (spos - fr + fp);
;                     vv[0] = (bf16_t)(p0 & 0xffff); vv[SEQ] = (bf16_t)(p0 >> 16); vv[2 * SEQ] = (bf16_t)(p1 & 0xffff); vv[3 * SEQ] = (bf16_t)(p1 >> 16); }
.LBB0_356:
	v_mov_b32_e32 v35, v34
	v_mov_b32_e32 v30, v34
	v_mov_b32_e32 v31, v34
	v_pk_mul_f32 v[26:27], v[26:27], v[34:35]
	s_and_b64 vcc, exec, s[42:43]
	s_mov_b64 s[6:7], -1
	v_pk_mul_f32 v[28:29], v[28:29], v[30:31]
	v_cvt_pk_bf16_f32 v26, v26, v27
	s_nop 0
	v_cvt_pk_bf16_f32 v27, v28, v29
	s_cbranch_vccnz .LBB0_358
	v_mov_b32_e32 v59, v65
	v_lshlrev_b64 v[28:29], 13, v[58:59]
	v_lshl_add_u64 v[28:29], v[90:91], 0, v[28:29]
	v_add_co_u32_e32 v30, vcc, 0x2000, v28
	ds_write_b16 v251, v26 offset:4352
	s_nop 0
	v_addc_co_u32_e32 v31, vcc, 0, v29, vcc
	ds_write_b16_d16_hi v251, v26 offset:4616
	v_add_co_u32_e32 v30, vcc, 0x4000, v28
	s_mov_b64 s[6:7], 0
	s_nop 0
	v_addc_co_u32_e32 v31, vcc, 0, v29, vcc
	v_add_co_u32_e32 v28, vcc, 0x6000, v28
	ds_write_b16 v251, v27 offset:4880
	s_nop 0
	v_addc_co_u32_e32 v29, vcc, 0, v29, vcc
	ds_write_b16_d16_hi v251, v27 offset:5144

; __device__ __forceinline__ unsigned pk2(float lo, float hi) { unsigned r; asm("v_cvt_pk_bf16_f32 %0, %1, %2" : "=v"(r) : "v"(lo), "v"(hi)); return r; }
; __device__ __forceinline__ void mixer_chunk(KP p, LAS unsigned char* lds, int l, int chunk) {
;     ...
;         for (int mt = 0; mt < 8; ++mt) {
;             const float rs = RSK[16 * mt + fr]; const int spos = s0 + 16 * mt + fr;
; #pragma unroll
;             for (int n = 0; n < 2; ++n) {
;                 const f32x4 a = acc[mt][n] * rs; const unsigned p0 = pk2(a[0], a[1]), p1 = pk2(a[2], a[3]);
;                 if ((w & 1) == 0) { u32x2 o; o.x = p0; o.y = p1; *(u32x2*)((bf16_t*)(ws + OFF_K) + ((size_t)(bidx * 4 + head) * SEQ + spos) * 96 + 16 * (2 * pz + n) + 4 * fq) = o; }
;                 else { const int fp = ((fr & 4) << 1) | ((fr & 8) >> 1) | (fr & 3);
;                     bf16_t* vv = (bf16_t*)(ws + OFF_VT) + ((size_t)(bidx * 4 + head) * 64 + 16 * (2 * pz + n) + 4 * fq) * SEQ + (spos - fr + fp);
;                     vv[0] = (bf16_t)(p0 & 0xffff); vv[SEQ] = (bf16_t)(p0 >> 16); vv[2 * SEQ] = (bf16_t)(p1 & 0xffff); vv[3 * SEQ] = (bf16_t)(p1 >> 16); }
.LBB0_360:
	ds_read_b32 v26, v107 offset:320
	s_and_b64 vcc, exec, s[42:43]
	s_mov_b64 s[6:7], -1
	s_waitcnt lgkmcnt(0)
	v_pk_mul_f32 v[22:23], v[22:23], v[26:27] op_sel_hi:[1,0]
	v_pk_mul_f32 v[24:25], v[24:25], v[26:27] op_sel_hi:[1,0]
	v_cvt_pk_bf16_f32 v22, v22, v23
	s_nop 0
	v_cvt_pk_bf16_f32 v23, v24, v25
	s_cbranch_vccnz .LBB0_362
	v_mov_b32_e32 v99, v65
	v_lshlrev_b64 v[24:25], 13, v[98:99]
	v_lshl_add_u64 v[24:25], v[92:93], 0, v[24:25]
	v_add_co_u32_e32 v28, vcc, 0x2000, v24
	ds_write_b16 v251, v22 offset:160
	s_nop 0
	v_addc_co_u32_e32 v29, vcc, 0, v25, vcc
	ds_write_b16_d16_hi v251, v22 offset:424
	v_add_co_u32_e32 v28, vcc, 0x4000, v24
	s_mov_b64 s[6:7], 0
	s_nop 0
	v_addc_co_u32_e32 v29, vcc, 0, v25, vcc
	v_add_co_u32_e32 v24, vcc, 0x6000, v24
	ds_write_b16 v251, v23 offset:688
	s_nop 0
	v_addc_co_u32_e32 v25, vcc, 0, v25, vcc
	ds_write_b16_d16_hi v251, v23 offset:952

; __device__ __forceinline__ unsigned pk2(float lo, float hi) { unsigned r; asm("v_cvt_pk_bf16_f32 %0, %1, %2" : "=v"(r) : "v"(lo), "v"(hi)); return r; }
; __device__ __forceinline__ void mixer_chunk(KP p, LAS unsigned char* lds, int l, int chunk) {
;     ...
;         for (int mt = 0; mt < 8; ++mt) {
;             const float rs = RSK[16 * mt + fr]; const int spos = s0 + 16 * mt + fr;
; #pragma unroll
;             for (int n = 0; n < 2; ++n) {
;                 const f32x4 a = acc[mt][n] * rs; const unsigned p0 = pk2(a[0], a[1]), p1 = pk2(a[2], a[3]);
;                 if ((w & 1) == 0) { u32x2 o; o.x = p0; o.y = p1; *(u32x2*)((bf16_t*)(ws + OFF_K) + ((size_t)(bidx * 4 + head) * SEQ + spos) * 96 + 16 * (2 * pz + n) + 4 * fq) = o; }
;                 else { const int fp = ((fr & 4) << 1) | ((fr & 8) >> 1) | (fr & 3);
;                     bf16_t* vv = (bf16_t*)(ws + OFF_VT) + ((size_t)(bidx * 4 + head) * 64 + 16 * (2 * pz + n) + 4 * fq) * SEQ + (spos - fr + fp);
;                     vv[0] = (bf16_t)(p0 & 0xffff); vv[SEQ] = (bf16_t)(p0 >> 16); vv[2 * SEQ] = (bf16_t)(p1 & 0xffff); vv[3 * SEQ] = (bf16_t)(p1 >> 16); }
.LBB0_364:
	v_mov_b32_e32 v27, v26
	v_mov_b32_e32 v22, v26
	v_mov_b32_e32 v23, v26
	v_pk_mul_f32 v[18:19], v[18:19], v[26:27]
	s_and_b64 vcc, exec, s[42:43]
	s_mov_b64 s[6:7], -1
	v_pk_mul_f32 v[20:21], v[20:21], v[22:23]
	v_cvt_pk_bf16_f32 v18, v18, v19
	s_nop 0
	v_cvt_pk_bf16_f32 v19, v20, v21
	s_cbranch_vccnz .LBB0_366
	v_mov_b32_e32 v59, v65
	v_lshlrev_b64 v[20:21], 13, v[58:59]
	v_lshl_add_u64 v[20:21], v[92:93], 0, v[20:21]
	v_add_co_u32_e32 v22, vcc, 0x2000, v20
	ds_write_b16 v251, v18 offset:4384
	s_nop 0
	v_addc_co_u32_e32 v23, vcc, 0, v21, vcc
	ds_write_b16_d16_hi v251, v18 offset:4648
	v_add_co_u32_e32 v22, vcc, 0x4000, v20
	s_mov_b64 s[6:7], 0
	s_nop 0
	v_addc_co_u32_e32 v23, vcc, 0, v21, vcc
	v_add_co_u32_e32 v20, vcc, 0x6000, v20
	ds_write_b16 v251, v19 offset:4912
	s_nop 0
	v_addc_co_u32_e32 v21, vcc, 0, v21, vcc
	ds_write_b16_d16_hi v251, v19 offset:5176

; __device__ __forceinline__ unsigned pk2(float lo, float hi) { unsigned r; asm("v_cvt_pk_bf16_f32 %0, %1, %2" : "=v"(r) : "v"(lo), "v"(hi)); return r; }
; __device__ __forceinline__ void mixer_chunk(KP p, LAS unsigned char* lds, int l, int chunk) {
;     ...
;         for (int mt = 0; mt < 8; ++mt) {
;             const float rs = RSK[16 * mt + fr]; const int spos = s0 + 16 * mt + fr;
; #pragma unroll
;             for (int n = 0; n < 2; ++n) {
;                 const f32x4 a = acc[mt][n] * rs; const unsigned p0 = pk2(a[0], a[1]), p1 = pk2(a[2], a[3]);
;                 if ((w & 1) == 0) { u32x2 o; o.x = p0; o.y = p1; *(u32x2*)((bf16_t*)(ws + OFF_K) + ((size_t)(bidx * 4 + head) * SEQ + spos) * 96 + 16 * (2 * pz + n) + 4 * fq) = o; }
;                 else { const int fp = ((fr & 4) << 1) | ((fr & 8) >> 1) | (fr & 3);
;                     bf16_t* vv = (bf16_t*)(ws + OFF_VT) + ((size_t)(bidx * 4 + head) * 64 + 16 * (2 * pz + n) + 4 * fq) * SEQ + (spos - fr + fp);
;                     vv[0] = (bf16_t)(p0 & 0xffff); vv[SEQ] = (bf16_t)(p0 >> 16); vv[2 * SEQ] = (bf16_t)(p1 & 0xffff); vv[3 * SEQ] = (bf16_t)(p1 >> 16); }
.LBB0_368:
	ds_read_b32 v18, v107 offset:384
	s_and_b64 vcc, exec, s[42:43]
	s_mov_b64 s[6:7], -1
	s_waitcnt lgkmcnt(0)
	v_pk_mul_f32 v[14:15], v[14:15], v[18:19] op_sel_hi:[1,0]
	v_pk_mul_f32 v[16:17], v[16:17], v[18:19] op_sel_hi:[1,0]
	v_cvt_pk_bf16_f32 v14, v14, v15
	s_nop 0
	v_cvt_pk_bf16_f32 v15, v16, v17
	s_cbranch_vccnz .LBB0_370
	v_mov_b32_e32 v99, v65
	v_lshlrev_b64 v[16:17], 13, v[98:99]
	v_lshl_add_u64 v[16:17], v[94:95], 0, v[16:17]
	v_add_co_u32_e32 v20, vcc, 0x2000, v16
	ds_write_b16 v251, v14 offset:192
	s_nop 0
	v_addc_co_u32_e32 v21, vcc, 0, v17, vcc
	ds_write_b16_d16_hi v251, v14 offset:456
	v_add_co_u32_e32 v20, vcc, 0x4000, v16
	s_mov_b64 s[6:7], 0
	s_nop 0
	v_addc_co_u32_e32 v21, vcc, 0, v17, vcc
	v_add_co_u32_e32 v16, vcc, 0x6000, v16
	ds_write_b16 v251, v15 offset:720
	s_nop 0
	v_addc_co_u32_e32 v17, vcc, 0, v17, vcc
	ds_write_b16_d16_hi v251, v15 offset:984

; __device__ __forceinline__ unsigned pk2(float lo, float hi) { unsigned r; asm("v_cvt_pk_bf16_f32 %0, %1, %2" : "=v"(r) : "v"(lo), "v"(hi)); return r; }
; __device__ __forceinline__ void mixer_chunk(KP p, LAS unsigned char* lds, int l, int chunk) {
;     ...
;         for (int mt = 0; mt < 8; ++mt) {
;             const float rs = RSK[16 * mt + fr]; const int spos = s0 + 16 * mt + fr;
; #pragma unroll
;             for (int n = 0; n < 2; ++n) {
;                 const f32x4 a = acc[mt][n] * rs; const unsigned p0 = pk2(a[0], a[1]), p1 = pk2(a[2], a[3]);
;                 if ((w & 1) == 0) { u32x2 o; o.x = p0; o.y = p1; *(u32x2*)((bf16_t*)(ws + OFF_K) + ((size_t)(bidx * 4 + head) * SEQ + spos) * 96 + 16 * (2 * pz + n) + 4 * fq) = o; }
;                 else { const int fp = ((fr & 4) << 1) | ((fr & 8) >> 1) | (fr & 3);
;                     bf16_t* vv = (bf16_t*)(ws + OFF_VT) + ((size_t)(bidx * 4 + head) * 64 + 16 * (2 * pz + n) + 4 * fq) * SEQ + (spos - fr + fp);
;                     vv[0] = (bf16_t)(p0 & 0xffff); vv[SEQ] = (bf16_t)(p0 >> 16); vv[2 * SEQ] = (bf16_t)(p1 & 0xffff); vv[3 * SEQ] = (bf16_t)(p1 >> 16); }
.LBB0_372:
	v_mov_b32_e32 v19, v18
	v_mov_b32_e32 v14, v18
	v_mov_b32_e32 v15, v18
	v_pk_mul_f32 v[10:11], v[10:11], v[18:19]
	s_and_b64 vcc, exec, s[42:43]
	s_mov_b64 s[6:7], -1
	v_pk_mul_f32 v[12:13], v[12:13], v[14:15]
	v_cvt_pk_bf16_f32 v10, v10, v11
	s_nop 0
	v_cvt_pk_bf16_f32 v11, v12, v13
	s_cbranch_vccnz .LBB0_374
	v_mov_b32_e32 v59, v65
	v_lshlrev_b64 v[12:13], 13, v[58:59]
	v_lshl_add_u64 v[12:13], v[94:95], 0, v[12:13]
	v_add_co_u32_e32 v14, vcc, 0x2000, v12
	ds_write_b16 v251, v10 offset:4416
	s_nop 0
	v_addc_co_u32_e32 v15, vcc, 0, v13, vcc
	ds_write_b16_d16_hi v251, v10 offset:4680
	v_add_co_u32_e32 v14, vcc, 0x4000, v12
	s_mov_b64 s[6:7], 0
	s_nop 0
	v_addc_co_u32_e32 v15, vcc, 0, v13, vcc
	v_add_co_u32_e32 v12, vcc, 0x6000, v12
	ds_write_b16 v251, v11 offset:4944
	s_nop 0
	v_addc_co_u32_e32 v13, vcc, 0, v13, vcc
	ds_write_b16_d16_hi v251, v11 offset:5208

; __device__ __forceinline__ unsigned pk2(float lo, float hi) { unsigned r; asm("v_cvt_pk_bf16_f32 %0, %1, %2" : "=v"(r) : "v"(lo), "v"(hi)); return r; }
; __device__ __forceinline__ void mixer_chunk(KP p, LAS unsigned char* lds, int l, int chunk) {
;     ...
;         for (int mt = 0; mt < 8; ++mt) {
;             const float rs = RSK[16 * mt + fr]; const int spos = s0 + 16 * mt + fr;
; #pragma unroll
;             for (int n = 0; n < 2; ++n) {
;                 const f32x4 a = acc[mt][n] * rs; const unsigned p0 = pk2(a[0], a[1]), p1 = pk2(a[2], a[3]);
;                 if ((w & 1) == 0) { u32x2 o; o.x = p0; o.y = p1; *(u32x2*)((bf16_t*)(ws + OFF_K) + ((size_t)(bidx * 4 + head) * SEQ + spos) * 96 + 16 * (2 * pz + n) + 4 * fq) = o; }
;                 else { const int fp = ((fr & 4) << 1) | ((fr & 8) >> 1) | (fr & 3);
;                     bf16_t* vv = (bf16_t*)(ws + OFF_VT) + ((size_t)(bidx * 4 + head) * 64 + 16 * (2 * pz + n) + 4 * fq) * SEQ + (spos - fr + fp);
;                     vv[0] = (bf16_t)(p0 & 0xffff); vv[SEQ] = (bf16_t)(p0 >> 16); vv[2 * SEQ] = (bf16_t)(p1 & 0xffff); vv[3 * SEQ] = (bf16_t)(p1 >> 16); }
.LBB0_376:
	ds_read_b32 v10, v107 offset:448
	s_and_b64 vcc, exec, s[42:43]
	s_mov_b64 s[6:7], -1
	s_waitcnt lgkmcnt(0)
	v_pk_mul_f32 v[6:7], v[6:7], v[10:11] op_sel_hi:[1,0]
	v_pk_mul_f32 v[8:9], v[8:9], v[10:11] op_sel_hi:[1,0]
	v_cvt_pk_bf16_f32 v6, v6, v7
	s_nop 0
	v_cvt_pk_bf16_f32 v7, v8, v9
	s_cbranch_vccnz .LBB0_378
	v_mov_b32_e32 v99, v65
	v_lshlrev_b64 v[8:9], 13, v[98:99]
	v_lshl_add_u64 v[8:9], v[96:97], 0, v[8:9]
	v_add_co_u32_e32 v12, vcc, 0x2000, v8
	ds_write_b16 v251, v6 offset:224
	s_nop 0
	v_addc_co_u32_e32 v13, vcc, 0, v9, vcc
	ds_write_b16_d16_hi v251, v6 offset:488
	v_add_co_u32_e32 v12, vcc, 0x4000, v8
	s_mov_b64 s[6:7], 0
	s_nop 0
	v_addc_co_u32_e32 v13, vcc, 0, v9, vcc
	v_add_co_u32_e32 v8, vcc, 0x6000, v8
	ds_write_b16 v251, v7 offset:752
	s_nop 0
	v_addc_co_u32_e32 v9, vcc, 0, v9, vcc
	ds_write_b16_d16_hi v251, v7 offset:1016

; __device__ __forceinline__ unsigned pk2(float lo, float hi) { unsigned r; asm("v_cvt_pk_bf16_f32 %0, %1, %2" : "=v"(r) : "v"(lo), "v"(hi)); return r; }
; __device__ __forceinline__ void mixer_chunk(KP p, LAS unsigned char* lds, int l, int chunk) {
;     ...
;         for (int mt = 0; mt < 8; ++mt) {
;             const float rs = RSK[16 * mt + fr]; const int spos = s0 + 16 * mt + fr;
; #pragma unroll
;             for (int n = 0; n < 2; ++n) {
;                 const f32x4 a = acc[mt][n] * rs; const unsigned p0 = pk2(a[0], a[1]), p1 = pk2(a[2], a[3]);
;                 if ((w & 1) == 0) { u32x2 o; o.x = p0; o.y = p1; *(u32x2*)((bf16_t*)(ws + OFF_K) + ((size_t)(bidx * 4 + head) * SEQ + spos) * 96 + 16 * (2 * pz + n) + 4 * fq) = o; }
;                 else { const int fp = ((fr & 4) << 1) | ((fr & 8) >> 1) | (fr & 3);
;                     bf16_t* vv = (bf16_t*)(ws + OFF_VT) + ((size_t)(bidx * 4 + head) * 64 + 16 * (2 * pz + n) + 4 * fq) * SEQ + (spos - fr + fp);
;                     vv[0] = (bf16_t)(p0 & 0xffff); vv[SEQ] = (bf16_t)(p0 >> 16); vv[2 * SEQ] = (bf16_t)(p1 & 0xffff); vv[3 * SEQ] = (bf16_t)(p1 >> 16); }
.LBB0_380:
	v_mov_b32_e32 v11, v10
	v_mov_b32_e32 v6, v10
	v_mov_b32_e32 v7, v10
	v_pk_mul_f32 v[2:3], v[2:3], v[10:11]
	s_and_b64 vcc, exec, s[42:43]
	s_mov_b64 s[6:7], -1
	v_pk_mul_f32 v[4:5], v[4:5], v[6:7]
	v_cvt_pk_bf16_f32 v2, v2, v3
	s_nop 0
	v_cvt_pk_bf16_f32 v3, v4, v5
	s_cbranch_vccnz .LBB0_382
	v_mov_b32_e32 v59, v65
	v_lshlrev_b64 v[4:5], 13, v[58:59]
	v_lshl_add_u64 v[4:5], v[96:97], 0, v[4:5]
	v_add_co_u32_e32 v6, vcc, 0x2000, v4
	ds_write_b16 v251, v2 offset:4448
	s_nop 0
	v_addc_co_u32_e32 v7, vcc, 0, v5, vcc
	ds_write_b16_d16_hi v251, v2 offset:4712
	v_add_co_u32_e32 v6, vcc, 0x4000, v4
	s_mov_b64 s[6:7], 0
	s_nop 0
	v_addc_co_u32_e32 v7, vcc, 0, v5, vcc
	v_add_co_u32_e32 v4, vcc, 0x6000, v4
	ds_write_b16 v251, v3 offset:4976
	s_nop 0
	v_addc_co_u32_e32 v5, vcc, 0, v5, vcc
	ds_write_b16_d16_hi v251, v3 offset:5240

; __device__ __forceinline__ unsigned pk2(float lo, float hi) { unsigned r; asm("v_cvt_pk_bf16_f32 %0, %1, %2" : "=v"(r) : "v"(lo), "v"(hi)); return r; }
; __device__ __forceinline__ void mixer_chunk(KP p, LAS unsigned char* lds, int l, int chunk) {
;     ...
;             for (int n = 0; n < 2; ++n) {
;                 const f32x4 a = acc[mt][n] * rs; const unsigned p0 = pk2(a[0], a[1]), p1 = pk2(a[2], a[3]);
;                 if ((w & 1) == 0) { u32x2 o; o.x = p0; o.y = p1; *(u32x2*)((bf16_t*)(ws + OFF_K) + ((size_t)(bidx * 4 + head) * SEQ + spos) * 96 + 16 * (2 * pz + n) + 4 * fq) = o; }
;                 else { const int fp = ((fr & 4) << 1) | ((fr & 8) >> 1) | (fr & 3);
;                     bf16_t* vv = (bf16_t*)(ws + OFF_VT) + ((size_t)(bidx * 4 + head) * 64 + 16 * (2 * pz + n) + 4 * fq) * SEQ + (spos - fr + fp);
;                     vv[0] = (bf16_t)(p0 & 0xffff); vv[SEQ] = (bf16_t)(p0 >> 16); vv[2 * SEQ] = (bf16_t)(p1 & 0xffff); vv[3 * SEQ] = (bf16_t)(p1 >> 16); }
;             }
;         }
;     }
.LBB0_384:
	s_and_b64 vcc, exec, s[90:91]
	s_cbranch_vccz .Lvt_done
	s_waitcnt lgkmcnt(0)
	v_and_b32_e32 v249, 63, v204
	v_lshrrev_b32_e32 v248, 4, v249
	v_and_b32_e32 v249, 15, v249
	v_mul_u32_u24_e32 v250, 264, v248
	v_lshl_add_u32 v250, v249, 4, v250
	v_lshrrev_b32_e32 v247, 7, v204
	v_mul_u32_u24_e32 v246, 0x4200, v247
	v_add_u32_e32 v250, v250, v246
	v_add_u32_e32 v250, 0x15800, v250
	v_lshlrev_b32_e32 v251, 13, v248
	v_lshl_add_u32 v251, v249, 4, v251
	v_readfirstlane_b32 s18, v247
	s_lshr_b32 s42, s23, 5
	s_lshl_b32 s42, s42, 2
	s_add_i32 s42, s42, s18
	s_lshl_b32 s42, s42, 19
	s_lshl_b32 s18, s24, 1
	s_add_i32 s42, s42, s18
	s_add_u32 s100, s94, 0x180b0000
	s_addc_u32 s101, s95, 0
	s_add_u32 s100, s100, s42
	s_addc_u32 s101, s101, 0
	ds_read_b64 v[234:235], v250 offset:0
	ds_read_b64 v[236:237], v250 offset:8
	ds_read_b64 v[238:239], v250 offset:1056
	ds_read_b64 v[240:241], v250 offset:1064
	ds_read_b64 v[242:243], v250 offset:2112
	ds_read_b64 v[244:245], v250 offset:2120
	ds_read_b64 v[246:247], v250 offset:3168
	ds_read_b64 v[248:249], v250 offset:3176
	s_waitcnt lgkmcnt(0)
	global_store_dwordx4 v251, v[234:237], s[100:101]
	s_add_u32 s100, s100, 0x8000
	s_addc_u32 s101, s101, 0
	global_store_dwordx4 v251, v[238:241], s[100:101]
	s_add_u32 s100, s100, 0x8000
	s_addc_u32 s101, s101, 0
	global_store_dwordx4 v251, v[242:245], s[100:101]
	s_add_u32 s100, s100, 0x8000
	s_addc_u32 s101, s101, 0
	global_store_dwordx4 v251, v[246:249], s[100:101]
	s_add_u32 s100, s100, 0x8000
	s_addc_u32 s101, s101, 0
	s_nop 1
	ds_read_b64 v[234:235], v250 offset:4224
	ds_read_b64 v[236:237], v250 offset:4232
	ds_read_b64 v[238:239], v250 offset:5280
	ds_read_b64 v[240:241], v250 offset:5288
	ds_read_b64 v[242:243], v250 offset:6336
	ds_read_b64 v[244:245], v250 offset:6344
	ds_read_b64 v[246:247], v250 offset:7392
	ds_read_b64 v[248:249], v250 offset:7400
	s_waitcnt lgkmcnt(0)
	global_store_dwordx4 v251, v[234:237], s[100:101]
	s_add_u32 s100, s100, 0x8000
	s_addc_u32 s101, s101, 0
	global_store_dwordx4 v251, v[238:241], s[100:101]
	s_add_u32 s100, s100, 0x8000
	s_addc_u32 s101, s101, 0
	global_store_dwordx4 v251, v[242:245], s[100:101]
	s_add_u32 s100, s100, 0x8000
	s_addc_u32 s101, s101, 0
	global_store_dwordx4 v251, v[246:249], s[100:101]
	s_add_u32 s100, s100, 0x8000
	s_addc_u32 s101, s101, 0
	s_nop 1
	ds_read_b64 v[234:235], v250 offset:8448
	ds_read_b64 v[236:237], v250 offset:8456
	ds_read_b64 v[238:239], v250 offset:9504
	ds_read_b64 v[240:241], v250 offset:9512
	ds_read_b64 v[242:243], v250 offset:10560
	ds_read_b64 v[244:245], v250 offset:10568
	ds_read_b64 v[246:247], v250 offset:11616
	ds_read_b64 v[248:249], v250 offset:11624
	s_waitcnt lgkmcnt(0)
	global_store_dwordx4 v251, v[234:237], s[100:101]
	s_add_u32 s100, s100, 0x8000
	s_addc_u32 s101, s101, 0
	global_store_dwordx4 v251, v[238:241], s[100:101]
	s_add_u32 s100, s100, 0x8000
	s_addc_u32 s101, s101, 0
	global_store_dwordx4 v251, v[242:245], s[100:101]
	s_add_u32 s100, s100, 0x8000
	s_addc_u32 s101, s101, 0
	global_store_dwordx4 v251, v[246:249], s[100:101]
	s_add_u32 s100, s100, 0x8000
	s_addc_u32 s101, s101, 0
	s_nop 1
	ds_read_b64 v[234:235], v250 offset:12672
	ds_read_b64 v[236:237], v250 offset:12680
	ds_read_b64 v[238:239], v250 offset:13728
	ds_read_b64 v[240:241], v250 offset:13736
	ds_read_b64 v[242:243], v250 offset:14784
	ds_read_b64 v[244:245], v250 offset:14792
	ds_read_b64 v[246:247], v250 offset:15840
	ds_read_b64 v[248:249], v250 offset:15848
	s_waitcnt lgkmcnt(0)
	global_store_dwordx4 v251, v[234:237], s[100:101]
	s_add_u32 s100, s100, 0x8000
	s_addc_u32 s101, s101, 0
	global_store_dwordx4 v251, v[238:241], s[100:101]
	s_add_u32 s100, s100, 0x8000
	s_addc_u32 s101, s101, 0
	global_store_dwordx4 v251, v[242:245], s[100:101]
	s_add_u32 s100, s100, 0x8000
	s_addc_u32 s101, s101, 0
	global_store_dwordx4 v251, v[246:249], s[100:101]
	s_add_u32 s100, s100, 0x8000
	s_addc_u32 s101, s101, 0
	s_nop 1

; __global__ void __launch_bounds__(512) fwd_kernel(Params p_arg) {
	.amdhsa_kernel _Z10fwd_kernel6Params
		.amdhsa_group_segment_fixed_size 0
		.amdhsa_private_segment_fixed_size 0
		.amdhsa_kernarg_size 472
		.amdhsa_user_sgpr_count 2
		.amdhsa_user_sgpr_dispatch_ptr 0
		.amdhsa_user_sgpr_queue_ptr 0
		.amdhsa_user_sgpr_kernarg_segment_ptr 1
		.amdhsa_user_sgpr_dispatch_id 0
		.amdhsa_user_sgpr_kernarg_preload_length 0
		.amdhsa_user_sgpr_kernarg_preload_offset 0
		.amdhsa_user_sgpr_private_segment_size 0
		.amdhsa_uses_dynamic_stack 0
		.amdhsa_enable_private_segment 0
		.amdhsa_system_sgpr_workgroup_id_x 1
		.amdhsa_system_sgpr_workgroup_id_y 0
		.amdhsa_system_sgpr_workgroup_id_z 0
		.amdhsa_system_sgpr_workgroup_info 0
		.amdhsa_system_vgpr_workitem_id 2
		.amdhsa_next_free_vgpr 255
		.amdhsa_next_free_sgpr 102
		.amdhsa_accum_offset 256
		.amdhsa_reserve_vcc 1
		.amdhsa_float_round_mode_32 0
		.amdhsa_float_round_mode_16_64 0
		.amdhsa_float_denorm_mode_32 3
		.amdhsa_float_denorm_mode_16_64 3
		.amdhsa_dx10_clamp 1
		.amdhsa_ieee_mode 1
		.amdhsa_fp16_overflow 0
		.amdhsa_tg_split 0
		.amdhsa_exception_fp_ieee_invalid_op 0
		.amdhsa_exception_fp_denorm_src 0
		.amdhsa_exception_fp_ieee_div_zero 0
		.amdhsa_exception_fp_ieee_overflow 0
		.amdhsa_exception_fp_ieee_underflow 0
		.amdhsa_exception_fp_ieee_inexact 0
		.amdhsa_exception_int_div_zero 0
	.end_amdhsa_kernel

; __global__ void __launch_bounds__(512) fwd_kernel(Params p_arg) {
amdhsa.kernels:
  - .agpr_count:     0
    .args:
      - .offset:         0
        .size:           216
        .value_kind:     by_value
      - .offset:         216
        .size:           4
        .value_kind:     hidden_block_count_x
      - .offset:         220
        .size:           4
        .value_kind:     hidden_block_count_y
      - .offset:         224
        .size:           4
        .value_kind:     hidden_block_count_z
      - .offset:         228
        .size:           2
        .value_kind:     hidden_group_size_x
      - .offset:         230
        .size:           2
        .value_kind:     hidden_group_size_y
      - .offset:         232
        .size:           2
        .value_kind:     hidden_group_size_z
      - .offset:         234
        .size:           2
        .value_kind:     hidden_remainder_x
      - .offset:         236
        .size:           2
        .value_kind:     hidden_remainder_y
      - .offset:         238
        .size:           2
        .value_kind:     hidden_remainder_z
      - .offset:         256
        .size:           8
        .value_kind:     hidden_global_offset_x
      - .offset:         264
        .size:           8
        .value_kind:     hidden_global_offset_y
      - .offset:         272
        .size:           8
        .value_kind:     hidden_global_offset_z
      - .offset:         280
        .size:           2
        .value_kind:     hidden_grid_dims
      - .offset:         304
        .size:           8
        .value_kind:     hidden_multigrid_sync_arg
      - .offset:         336
        .size:           4
        .value_kind:     hidden_dynamic_lds_size
    .group_segment_fixed_size: 0
    .kernarg_segment_align: 8
    .kernarg_segment_size: 472
    .language:       OpenCL C
    .language_version:
      - 2
      - 0
    .max_flat_workgroup_size: 512
    .name:           _Z10fwd_kernel6Params
    .private_segment_fixed_size: 0
    .sgpr_count:     108
    .sgpr_spill_count: 146
    .symbol:         _Z10fwd_kernel6Params.kd
    .uniform_work_group_size: 1
    .uses_dynamic_stack: false
    .vgpr_count:     255
    .vgpr_spill_count: 0
    .wavefront_size: 64
